# WIN loop: LDS-DMA double-buffered staging as in the SEL loop
# baseline (speedup 1.0000x reference)
.LBB0_1656:
	v_mov_b32_e32 v4, v220
	s_lshl_b64 s[0:1], s[66:67], 21
	v_ashrrev_i32_e32 v0, 6, v4
	s_waitcnt lgkmcnt(0)
	v_lshl_add_u32 v2, v0, 3, s76
	v_lshrrev_b32_e32 v3, 2, v4
	v_and_or_b32 v2, v3, 3, v2
	v_and_or_b32 v1, v4, 3, s7
	v_mul_lo_u32 v2, v2, 48
	s_waitcnt vmcnt(0)
	v_mad_u32_u24 v14, v1, 3, v2
	v_ashrrev_i32_e32 v15, 31, v14
	v_lshl_add_u64 v[2:3], v[14:15], 2, s[62:63]
	global_load_dword v16, v[2:3], off offset:4
	v_ashrrev_i32_e32 v1, 31, v0
	v_lshlrev_b64 v[0:1], 6, v[0:1]
	v_lshl_add_u64 v[0:1], v[0:1], 0, s[58:59]
	v_and_or_b32 v0, v4, 63, v0
	v_lshlrev_b64 v[0:1], 8, v[0:1]
	v_lshl_add_u64 v[0:1], s[64:65], 0, v[0:1]
	global_load_dwordx4 v[2:5], v[0:1], off
	global_load_dwordx4 v[6:9], v[0:1], off offset:16
	global_load_dwordx4 v[10:13], v[0:1], off offset:32
	global_load_dwordx4 v[116:119], v[0:1], off offset:48
	global_load_dwordx4 v[120:123], v[0:1], off offset:64
	global_load_dwordx4 v[124:127], v[0:1], off offset:80
	global_load_dwordx4 v[128:131], v[0:1], off offset:96
	global_load_dwordx4 v[132:135], v[0:1], off offset:112
	v_mov_b32_e32 v15, v176
	s_nop 1
	v_permlane32_swap_b32_e32 v176, v15
	v_add_f32_e32 v15, v176, v15
	v_mov_b32_e32 v18, v15
	s_nop 1
	v_permlane16_swap_b32_e32 v15, v18
	v_add_f32_e32 v18, v15, v18
	v_add_u32_e32 v14, 0xc0, v14
	v_ashrrev_i32_e32 v15, 31, v14
	v_lshl_add_u64 v[14:15], v[14:15], 2, s[62:63]
	s_waitcnt vmcnt(8)
	v_div_scale_f32 v19, s[10:11], v18, v18, v16
	v_rcp_f32_e32 v136, v19
	v_div_scale_f32 v137, vcc, v16, v18, v16
	s_max_i32 s10, s77, 0x1ff
	v_fma_f32 v138, -v19, v136, 1.0
	v_fmac_f32_e32 v136, v138, v136
	v_mul_f32_e32 v138, v137, v136
	v_fma_f32 v139, -v19, v138, v137
	v_fmac_f32_e32 v138, v139, v136
	v_fma_f32 v19, -v19, v138, v137
	v_div_fmas_f32 v19, v19, v136, v138
	v_div_fixup_f32 v16, v19, v18, v16
	s_waitcnt vmcnt(7)
	v_pk_fma_f32 v[4:5], v[114:115], v[16:17], v[4:5] op_sel_hi:[1,0,1]
	v_pk_fma_f32 v[2:3], v[112:113], v[16:17], v[2:3] op_sel_hi:[1,0,1]
	s_waitcnt vmcnt(6)
	v_pk_fma_f32 v[8:9], v[110:111], v[16:17], v[8:9] op_sel_hi:[1,0,1]
	v_pk_fma_f32 v[6:7], v[108:109], v[16:17], v[6:7] op_sel_hi:[1,0,1]
	s_waitcnt vmcnt(5)
	v_pk_fma_f32 v[12:13], v[106:107], v[16:17], v[12:13] op_sel_hi:[1,0,1]
	v_pk_fma_f32 v[10:11], v[104:105], v[16:17], v[10:11] op_sel_hi:[1,0,1]
	s_waitcnt vmcnt(4)
	v_pk_fma_f32 v[102:103], v[102:103], v[16:17], v[118:119] op_sel_hi:[1,0,1]
	v_pk_fma_f32 v[100:101], v[100:101], v[16:17], v[116:117] op_sel_hi:[1,0,1]
	s_waitcnt vmcnt(3)
	v_pk_fma_f32 v[98:99], v[98:99], v[16:17], v[122:123] op_sel_hi:[1,0,1]
	v_pk_fma_f32 v[96:97], v[96:97], v[16:17], v[120:121] op_sel_hi:[1,0,1]
	s_waitcnt vmcnt(2)
	v_pk_fma_f32 v[94:95], v[94:95], v[16:17], v[126:127] op_sel_hi:[1,0,1]
	v_pk_fma_f32 v[92:93], v[92:93], v[16:17], v[124:125] op_sel_hi:[1,0,1]
	s_waitcnt vmcnt(1)
	v_pk_fma_f32 v[90:91], v[90:91], v[16:17], v[130:131] op_sel_hi:[1,0,1]
	v_pk_fma_f32 v[88:89], v[88:89], v[16:17], v[128:129] op_sel_hi:[1,0,1]
	s_waitcnt vmcnt(0)
	v_pk_fma_f32 v[86:87], v[86:87], v[16:17], v[134:135] op_sel_hi:[1,0,1]
	v_pk_fma_f32 v[84:85], v[84:85], v[16:17], v[132:133] op_sel_hi:[1,0,1]
	global_store_dwordx4 v[0:1], v[2:5], off
	global_store_dwordx4 v[0:1], v[6:9], off offset:16
	global_store_dwordx4 v[0:1], v[10:13], off offset:32
	global_store_dwordx4 v[0:1], v[100:103], off offset:48
	global_store_dwordx4 v[0:1], v[96:99], off offset:64
	global_store_dwordx4 v[0:1], v[92:95], off offset:80
	global_store_dwordx4 v[0:1], v[88:91], off offset:96
	global_store_dwordx4 v[0:1], v[84:87], off offset:112
	global_load_dword v3, v[14:15], off offset:4
	global_load_dwordx4 v[4:7], v[0:1], off offset:128
	global_load_dwordx4 v[8:11], v[0:1], off offset:144
	s_nop 0
	global_load_dwordx4 v[12:15], v[0:1], off offset:160
	global_load_dwordx4 v[84:87], v[0:1], off offset:176
	global_load_dwordx4 v[88:91], v[0:1], off offset:192
	global_load_dwordx4 v[92:95], v[0:1], off offset:208
	global_load_dwordx4 v[96:99], v[0:1], off offset:224
	global_load_dwordx4 v[100:103], v[0:1], off offset:240
	v_mov_b32_e32 v16, v175
	s_nop 1
	v_permlane32_swap_b32_e32 v175, v16
	v_add_f32_e32 v16, v175, v16
	v_mov_b32_e32 v18, v16
	s_nop 1
	v_permlane16_swap_b32_e32 v16, v18
	v_add_f32_e32 v16, v16, v18
	s_addk_i32 s10, 0xfe01
	s_lshr_b32 s10, s10, 6
	v_mov_b32_e32 v2, v220
	s_cmp_gt_i32 s10, s86
	s_waitcnt vmcnt(8)
	v_div_scale_f32 v18, s[12:13], v16, v16, v3
	v_rcp_f32_e32 v19, v18
	v_div_scale_f32 v104, vcc, v3, v16, v3
	v_fma_f32 v105, -v18, v19, 1.0
	v_fmac_f32_e32 v19, v105, v19
	v_mul_f32_e32 v105, v104, v19
	v_fma_f32 v106, -v18, v105, v104
	v_fmac_f32_e32 v105, v106, v19
	v_fma_f32 v18, -v18, v105, v104
	v_div_fmas_f32 v18, v18, v19, v105
	v_div_fixup_f32 v16, v18, v16, v3
	s_waitcnt vmcnt(7)
	v_pk_fma_f32 v[6:7], v[82:83], v[16:17], v[6:7] op_sel_hi:[1,0,1]
	v_pk_fma_f32 v[4:5], v[80:81], v[16:17], v[4:5] op_sel_hi:[1,0,1]
	s_waitcnt vmcnt(6)
	v_pk_fma_f32 v[10:11], v[78:79], v[16:17], v[10:11] op_sel_hi:[1,0,1]
	v_pk_fma_f32 v[8:9], v[76:77], v[16:17], v[8:9] op_sel_hi:[1,0,1]
	s_waitcnt vmcnt(5)
	v_pk_fma_f32 v[14:15], v[74:75], v[16:17], v[14:15] op_sel_hi:[1,0,1]
	v_pk_fma_f32 v[12:13], v[72:73], v[16:17], v[12:13] op_sel_hi:[1,0,1]
	s_waitcnt vmcnt(4)
	v_pk_fma_f32 v[70:71], v[70:71], v[16:17], v[86:87] op_sel_hi:[1,0,1]
	v_pk_fma_f32 v[68:69], v[68:69], v[16:17], v[84:85] op_sel_hi:[1,0,1]
	s_waitcnt vmcnt(3)
	v_pk_fma_f32 v[64:65], v[64:65], v[16:17], v[88:89] op_sel_hi:[1,0,1]
	v_pk_fma_f32 v[66:67], v[66:67], v[16:17], v[90:91] op_sel_hi:[1,0,1]
	s_waitcnt vmcnt(2)
	v_pk_fma_f32 v[60:61], v[60:61], v[16:17], v[92:93] op_sel_hi:[1,0,1]
	v_pk_fma_f32 v[62:63], v[62:63], v[16:17], v[94:95] op_sel_hi:[1,0,1]
	s_waitcnt vmcnt(1)
	v_pk_fma_f32 v[56:57], v[56:57], v[16:17], v[96:97] op_sel_hi:[1,0,1]
	v_pk_fma_f32 v[58:59], v[58:59], v[16:17], v[98:99] op_sel_hi:[1,0,1]
	s_waitcnt vmcnt(0)
	v_pk_fma_f32 v[52:53], v[52:53], v[16:17], v[100:101] op_sel_hi:[1,0,1]
	v_pk_fma_f32 v[54:55], v[54:55], v[16:17], v[102:103] op_sel_hi:[1,0,1]
	global_store_dwordx4 v[0:1], v[4:7], off offset:128
	global_store_dwordx4 v[0:1], v[8:11], off offset:144
	global_store_dwordx4 v[0:1], v[12:15], off offset:160
	global_store_dwordx4 v[0:1], v[68:71], off offset:176
	global_store_dwordx4 v[0:1], v[64:67], off offset:192
	global_store_dwordx4 v[0:1], v[60:63], off offset:208
	global_store_dwordx4 v[0:1], v[56:59], off offset:224
	global_store_dwordx4 v[0:1], v[52:55], off offset:240
	s_cbranch_scc1 .LBB0_1466
	s_lshl_b64 s[12:13], s[0:1], 1
	v_readlane_b32 s0, v254, 22
	s_add_u32 s0, s0, s12
	v_readlane_b32 s1, v254, 26
	s_addc_u32 s1, s1, s13
	s_add_u32 s12, s96, s12
	v_lshrrev_b32_e32 v0, 3, v2
	s_mov_b32 s11, s57
	s_addc_u32 s13, s97, s13
	v_ashrrev_i32_e32 v6, 2, v2
	v_and_b32_e32 v0, 12, v0
	s_lshl_b64 s[14:15], s[10:11], 14
	v_and_or_b32 v7, v6, 3, v0
	s_add_u32 s16, s12, s14
	v_lshlrev_b32_e32 v0, 5, v2
	s_addc_u32 s17, s13, s15
	v_ashrrev_i32_e32 v1, 31, v0
	v_mov_b64_e32 v[0:1], v[252:253]
	s_add_u32 s14, s0, s14
	s_addc_u32 s15, s1, s15
	v_lshlrev_b32_e32 v5, 2, v2
	v_lshlrev_b32_e32 v4, 4, v6
	v_and_b32_e32 v6, 12, v5
	v_bitop3_b32 v11, v7, v4, v6 bitop3:0xde
	v_lshlrev_b32_e32 v156, 4, v11
	v_or_b32_e32 v11, 1, v6
	v_bitop3_b32 v11, v11, v4, v7 bitop3:0xde
	v_lshlrev_b32_e32 v157, 4, v11
	v_or_b32_e32 v11, 2, v6
	v_or_b32_e32 v6, 3, v6
	v_bfe_u32 v3, v2, 2, 3
	v_bitop3_b32 v11, v11, v4, v7 bitop3:0xde
	v_bitop3_b32 v4, v6, v4, v7 bitop3:0xde
	v_lshlrev_b32_e32 v159, 4, v4
	v_and_b32_e32 v4, -8, v5
	v_and_b32_e32 v6, 4, v5
	v_bitop3_b32 v5, v5, v3, 4 bitop3:0x6c
	v_or_b32_e32 v5, v5, v4
	v_lshlrev_b32_e32 v160, 4, v5
	v_bitop3_b32 v5, v6, v3, 1 bitop3:0x36
	v_or_b32_e32 v5, v5, v4
	v_lshlrev_b32_e32 v161, 4, v5
	v_bitop3_b32 v5, v6, v3, 2 bitop3:0x36
	v_bitop3_b32 v3, v6, v3, 3 bitop3:0x36
	v_lshl_add_u64 v[152:153], s[12:13], 0, v[0:1]
	v_lshl_add_u64 v[154:155], s[0:1], 0, v[0:1]
	v_ashrrev_i32_e32 v0, 3, v2
	v_lshrrev_b32_e32 v8, 4, v2
	v_bfe_u32 v9, v2, 4, 2
	v_and_b32_e32 v10, 15, v2
	v_or_b32_e32 v5, v5, v4
	v_or_b32_e32 v3, v3, v4
	v_and_b32_e32 v0, -8, v0
	v_lshlrev_b32_e32 v162, 4, v5
	v_lshlrev_b32_e32 v163, 4, v3
	v_add_u32_e32 v164, s77, v0
	v_and_b32_e32 v0, 12, v2
	v_bitop3_b32 v1, v8, v10, 3 bitop3:0x6c
	v_bitop3_b32 v3, v9, v10, 4 bitop3:0x36
	v_bitop3_b32 v4, v9, v10, 8 bitop3:0x36
	v_bitop3_b32 v5, v9, v10, 12 bitop3:0x36
	v_add_lshl_u32 v0, v0, v10, 8
	v_lshlrev_b32_e32 v1, 4, v1
	v_lshlrev_b32_e32 v3, 4, v3
	v_lshlrev_b32_e32 v4, 4, v4
	v_lshlrev_b32_e32 v5, 4, v5
	v_or_b32_e32 v165, v1, v0
	v_or_b32_e32 v167, v3, v0
	v_or_b32_e32 v176, v4, v0
	v_or_b32_e32 v178, v5, v0
	v_or_b32_e32 v0, 0x2000, v0
	v_or3_b32 v180, v1, v0, s8
	v_or3_b32 v181, v3, v0, s8
	v_or3_b32 v182, v4, v0, s8
	v_or3_b32 v183, v5, v0, s8
	v_bfe_u32 v0, v2, 2, 2
	v_or_b32_e32 v185, v164, v0
	v_bfe_u32 v0, v2, 1, 3
	v_bitop3_b32 v1, v8, v0, 3 bitop3:0x6c
	v_bitop3_b32 v0, v9, v0, 4 bitop3:0x36
	v_mov_b32_e32 v18, v17
	v_mov_b32_e32 v19, v17
	v_lshlrev_b32_e32 v2, 7, v10
	v_lshlrev_b32_e32 v1, 4, v1
	v_lshlrev_b32_e32 v0, 4, v0
	v_mov_b32_e32 v16, v17
	v_mov_b64_e32 v[54:55], v[18:19]
	v_mov_b64_e32 v[58:59], v[18:19]
	v_mov_b64_e32 v[62:63], v[18:19]
	v_mov_b64_e32 v[66:67], v[18:19]
	v_mov_b64_e32 v[70:71], v[18:19]
	v_mov_b64_e32 v[74:75], v[18:19]
	v_mov_b64_e32 v[78:79], v[18:19]
	v_mov_b64_e32 v[82:83], v[18:19]
	v_mov_b64_e32 v[86:87], v[18:19]
	v_mov_b64_e32 v[90:91], v[18:19]
	v_mov_b64_e32 v[94:95], v[18:19]
	v_mov_b64_e32 v[98:99], v[18:19]
	v_mov_b64_e32 v[102:103], v[18:19]
	v_mov_b64_e32 v[106:107], v[18:19]
	v_mov_b64_e32 v[110:111], v[18:19]
	v_mov_b64_e32 v[114:115], v[18:19]
	v_lshlrev_b32_e32 v158, 4, v11
	v_or_b32_e32 v166, 0x400, v165
	v_or_b32_e32 v175, 0x400, v167
	v_or_b32_e32 v177, 0x400, v176
	v_or_b32_e32 v179, 0x400, v178
	v_add_u32_e32 v184, 0xfffffe03, v164
	v_add_u32_e32 v186, 0xfffffe00, v185
	v_lshlrev_b32_e32 v187, 3, v9
	v_add_u32_e32 v188, 0xfffffe07, v164
	v_or_b32_e32 v189, 4, v185
	v_add_u32_e32 v190, 0xfffffe04, v185
	s_lshl_b32 s11, s10, 6
	v_mov_b32_e32 v193, 0
	v_mov_b32_e32 v194, 0xf149f2ca
	v_add_u32_e32 v191, v2, v1
	v_add_u32_e32 v192, v2, v0
	v_mov_b64_e32 v[52:53], v[16:17]
	v_mov_b64_e32 v[56:57], v[16:17]
	v_mov_b64_e32 v[60:61], v[16:17]
	v_mov_b64_e32 v[64:65], v[16:17]
	v_mov_b64_e32 v[68:69], v[16:17]
	v_mov_b64_e32 v[72:73], v[16:17]
	v_mov_b64_e32 v[76:77], v[16:17]
	v_mov_b64_e32 v[80:81], v[16:17]
	v_mov_b64_e32 v[84:85], v[16:17]
	v_mov_b64_e32 v[88:89], v[16:17]
	v_mov_b64_e32 v[92:93], v[16:17]
	v_mov_b64_e32 v[96:97], v[16:17]
	v_mov_b64_e32 v[100:101], v[16:17]
	v_mov_b64_e32 v[104:105], v[16:17]
	v_mov_b64_e32 v[108:109], v[16:17]
	v_mov_b64_e32 v[112:113], v[16:17]
	v_mov_b32_e32 v16, 0xf149f2ca
	v_mov_b32_e32 v19, 0
	v_mov_b32_e32 v143, 0
	v_mov_b32_e32 v142, v249
	v_lshl_add_u64 v[116:117], s[12:13], 0, v[142:143]
	v_add_u32_e32 v142, 0x1000, v250
	v_lshl_add_u64 v[118:119], s[12:13], 0, v[142:143]
	v_add_u32_e32 v142, 0x2000, v249
	v_lshl_add_u64 v[120:121], s[12:13], 0, v[142:143]
	v_add_u32_e32 v142, 0x3000, v250
	v_lshl_add_u64 v[122:123], s[12:13], 0, v[142:143]
	v_mov_b32_e32 v142, v251
	v_lshl_add_u64 v[128:129], s[0:1], 0, v[142:143]
	v_add_u32_e32 v142, 0x1000, v251
	v_lshl_add_u64 v[130:131], s[0:1], 0, v[142:143]
	v_add_u32_e32 v142, 0x2000, v251
	v_lshl_add_u64 v[136:137], s[0:1], 0, v[142:143]
	v_add_u32_e32 v142, 0x3000, v251
	v_lshl_add_u64 v[138:139], s[0:1], 0, v[142:143]
	v_lshrrev_b32_e32 v143, 6, v220
	v_lshlrev_b32_e32 v143, 10, v143
	s_lshl_b32 s14, s10, 14
	s_mov_b32 s15, 0
	v_readfirstlane_b32 vcc_lo, v143
	s_mov_b32 m0, vcc_lo
	v_lshl_add_u64 v[140:141], v[116:117], 0, s[14:15]
	global_load_lds_dwordx4 v[140:141], off
	s_add_u32 m0, m0, 0x1000
	v_lshl_add_u64 v[140:141], v[118:119], 0, s[14:15]
	global_load_lds_dwordx4 v[140:141], off
	s_add_u32 m0, m0, 0x1000
	v_lshl_add_u64 v[140:141], v[120:121], 0, s[14:15]
	global_load_lds_dwordx4 v[140:141], off
	s_add_u32 m0, m0, 0x1000
	v_lshl_add_u64 v[140:141], v[122:123], 0, s[14:15]
	global_load_lds_dwordx4 v[140:141], off
	s_add_u32 m0, m0, 0x1000
	v_lshl_add_u64 v[140:141], v[128:129], 0, s[14:15]
	global_load_lds_dwordx4 v[140:141], off
	s_add_u32 m0, m0, 0x1000
	v_lshl_add_u64 v[140:141], v[130:131], 0, s[14:15]
	global_load_lds_dwordx4 v[140:141], off
	s_add_u32 m0, m0, 0x1000
	v_lshl_add_u64 v[140:141], v[136:137], 0, s[14:15]
	global_load_lds_dwordx4 v[140:141], off
	s_add_u32 m0, m0, 0x1000
	v_lshl_add_u64 v[140:141], v[138:139], 0, s[14:15]
	global_load_lds_dwordx4 v[140:141], off
.LBB0_1658:
	s_waitcnt vmcnt(0) lgkmcnt(0)
	s_barrier
	ds_read_b128 v[0:3], v165
	ds_read_b128 v[4:7], v166
	ds_read_b128 v[8:11], v167
	ds_read_b128 v[12:15], v175
	ds_read_b128 v[124:127], v176
	ds_read_b128 v[132:135], v177
	ds_read_b128 v[144:147], v178
	ds_read_b128 v[148:151], v179
	s_waitcnt lgkmcnt(7)
	v_mfma_f32_16x16x32_bf16 v[0:3], v[0:3], v[20:23], 0
	s_mov_b32 s0, s10
	s_add_i32 s10, s10, 1
	s_cmp_ge_i32 s0, s86
	s_waitcnt lgkmcnt(6)
	v_mfma_f32_16x16x32_bf16 v[4:7], v[4:7], v[20:23], 0
	s_cselect_b64 s[12:13], -1, 0
	s_cmp_lt_i32 s0, s86
	s_cselect_b32 s56, s10, s0
	s_waitcnt lgkmcnt(5)
	v_mfma_f32_16x16x32_bf16 v[0:3], v[8:11], v[24:27], v[0:3]
	s_lshl_b64 s[0:1], s[56:57], 14
	v_readfirstlane_b32 vcc_lo, v143
	s_add_i32 m0, vcc_lo, 0x8000
	v_lshl_add_u64 v[140:141], v[116:117], 0, s[0:1]
	global_load_lds_dwordx4 v[140:141], off
	s_add_u32 m0, m0, 0x1000
	v_lshl_add_u64 v[140:141], v[118:119], 0, s[0:1]
	global_load_lds_dwordx4 v[140:141], off
	s_add_u32 m0, m0, 0x1000
	v_lshl_add_u64 v[140:141], v[120:121], 0, s[0:1]
	global_load_lds_dwordx4 v[140:141], off
	s_add_u32 m0, m0, 0x1000
	v_lshl_add_u64 v[140:141], v[122:123], 0, s[0:1]
	global_load_lds_dwordx4 v[140:141], off
	s_add_u32 m0, m0, 0x1000
	v_lshl_add_u64 v[140:141], v[128:129], 0, s[0:1]
	global_load_lds_dwordx4 v[140:141], off
	s_add_u32 m0, m0, 0x1000
	v_lshl_add_u64 v[140:141], v[130:131], 0, s[0:1]
	global_load_lds_dwordx4 v[140:141], off
	s_add_u32 m0, m0, 0x1000
	v_lshl_add_u64 v[140:141], v[136:137], 0, s[0:1]
	global_load_lds_dwordx4 v[140:141], off
	s_add_u32 m0, m0, 0x1000
	v_lshl_add_u64 v[140:141], v[138:139], 0, s[0:1]
	global_load_lds_dwordx4 v[140:141], off
	s_waitcnt lgkmcnt(4)
	v_mfma_f32_16x16x32_bf16 v[4:7], v[12:15], v[24:27], v[4:7]
	s_waitcnt lgkmcnt(3)
	v_mfma_f32_16x16x32_bf16 v[0:3], v[124:127], v[28:31], v[0:3]
	s_waitcnt lgkmcnt(2)
	v_mfma_f32_16x16x32_bf16 v[10:13], v[132:135], v[28:31], v[4:7]
	s_waitcnt lgkmcnt(1)
	v_mfma_f32_16x16x32_bf16 v[6:9], v[144:147], v[32:35], v[0:3]
	s_waitcnt lgkmcnt(0)
	v_mfma_f32_16x16x32_bf16 v[2:5], v[148:151], v[32:35], v[10:13]
	s_nop 2
	ds_read_b128 v[10:13], v165 offset:8192
	ds_read_b128 v[148:151], v180
	ds_read_b128 v[196:199], v167 offset:8192
	ds_read_b128 v[200:203], v181
	ds_read_b128 v[204:207], v176 offset:8192
	ds_read_b128 v[208:211], v182
	ds_read_b128 v[212:215], v178 offset:8192
	ds_read_b128 v[216:219], v183
	s_waitcnt lgkmcnt(7)
	v_mfma_f32_16x16x32_bf16 v[10:13], v[10:13], v[20:23], 0
	s_waitcnt lgkmcnt(6)
	v_mfma_f32_16x16x32_bf16 v[148:151], v[148:151], v[20:23], 0
	s_waitcnt lgkmcnt(5)
	v_mfma_f32_16x16x32_bf16 v[10:13], v[196:199], v[24:27], v[10:13]
	s_waitcnt lgkmcnt(4)
	v_mfma_f32_16x16x32_bf16 v[148:151], v[200:203], v[24:27], v[148:151]
	s_waitcnt lgkmcnt(3)
	v_mfma_f32_16x16x32_bf16 v[10:13], v[204:207], v[28:31], v[10:13]
	s_waitcnt lgkmcnt(2)
	v_mfma_f32_16x16x32_bf16 v[196:199], v[208:211], v[28:31], v[148:151]
	s_waitcnt lgkmcnt(1)
	v_mfma_f32_16x16x32_bf16 v[148:151], v[212:215], v[32:35], v[10:13]
	s_waitcnt lgkmcnt(0)
	v_mfma_f32_16x16x32_bf16 v[10:13], v[216:219], v[32:35], v[196:199]
	s_add_i32 s0, s11, 63
	v_cmp_gt_i32_e32 vcc, s0, v164
	v_cmp_le_i32_e64 s[0:1], s11, v184
	v_add_u32_e32 v205, s11, v187
	s_or_b64 s[14:15], vcc, s[0:1]
	s_and_saveexec_b64 s[26:27], s[14:15]
	s_xor_b64 s[26:27], exec, s[26:27]
	s_cbranch_execz .LBB0_1660
	v_add_u32_e32 v209, 2, v205
	v_add_u32_e32 v208, 3, v205
	v_add_u32_e32 v207, 4, v205
	v_add_u32_e32 v206, 5, v205
	v_add_u32_e32 v204, 6, v205
	v_add_u32_e32 v203, 7, v205
	v_add_u32_e32 v202, 32, v205
	v_add_u32_e32 v201, 34, v205
	v_add_u32_e32 v200, 35, v205
	v_add_u32_e32 v199, 36, v205
	v_add_u32_e32 v198, 37, v205
	v_add_u32_e32 v197, 38, v205
	v_add_u32_e32 v18, 39, v205
	v_cmp_gt_i32_e32 vcc, v205, v186
	v_cmp_le_i32_e64 s[0:1], v205, v185
	s_and_b64 s[16:17], vcc, s[0:1]
	v_cmp_ge_i32_e32 vcc, v205, v186
	v_cmp_lt_i32_e64 s[0:1], v205, v185
	s_and_b64 s[18:19], vcc, s[0:1]
	v_cmp_gt_i32_e32 vcc, v209, v186
	v_cmp_le_i32_e64 s[0:1], v209, v185
	s_and_b64 s[20:21], vcc, s[0:1]
	v_cmp_gt_i32_e32 vcc, v208, v186
	v_cmp_le_i32_e64 s[0:1], v208, v185
	s_and_b64 s[22:23], vcc, s[0:1]
	v_cmp_gt_i32_e32 vcc, v207, v186
	v_cmp_le_i32_e64 s[0:1], v207, v185
	s_and_b64 s[24:25], vcc, s[0:1]
	v_cmp_gt_i32_e32 vcc, v206, v186
	v_cmp_le_i32_e64 s[0:1], v206, v185
	s_and_b64 s[28:29], vcc, s[0:1]
	v_cmp_gt_i32_e32 vcc, v204, v186
	v_cmp_le_i32_e64 s[0:1], v204, v185
	s_and_b64 s[30:31], vcc, s[0:1]
	v_cmp_gt_i32_e32 vcc, v203, v186
	v_cmp_le_i32_e64 s[0:1], v203, v185
	s_and_b64 s[34:35], vcc, s[0:1]
	v_cmp_gt_i32_e32 vcc, v202, v186
	v_cmp_le_i32_e64 s[0:1], v202, v185
	s_and_b64 s[36:37], vcc, s[0:1]
	v_cmp_ge_i32_e32 vcc, v202, v186
	v_cmp_lt_i32_e64 s[0:1], v202, v185
	s_and_b64 s[38:39], vcc, s[0:1]
	v_cmp_gt_i32_e32 vcc, v201, v186
	v_cmp_le_i32_e64 s[0:1], v201, v185
	s_and_b64 s[40:41], vcc, s[0:1]
	v_cmp_gt_i32_e32 vcc, v200, v186
	v_cmp_le_i32_e64 s[0:1], v200, v185
	s_and_b64 s[42:43], vcc, s[0:1]
	v_cmp_gt_i32_e32 vcc, v199, v186
	v_cmp_le_i32_e64 s[0:1], v199, v185
	s_and_b64 s[44:45], vcc, s[0:1]
	v_cmp_gt_i32_e32 vcc, v198, v186
	v_cmp_le_i32_e64 s[0:1], v198, v185
	s_and_b64 s[46:47], vcc, s[0:1]
	v_cmp_gt_i32_e32 vcc, v197, v186
	v_cmp_le_i32_e64 s[0:1], v197, v185
	s_and_b64 s[48:49], vcc, s[0:1]
	v_cmp_gt_i32_e32 vcc, v18, v186
	v_cmp_le_i32_e64 s[0:1], v18, v185
	s_and_b64 s[0:1], vcc, s[0:1]
	v_cndmask_b32_e64 v6, v169, v6, s[16:17]
	v_cndmask_b32_e64 v7, v169, v7, s[18:19]
	v_cndmask_b32_e64 v8, v169, v8, s[20:21]
	v_cndmask_b32_e64 v9, v169, v9, s[22:23]
	v_cndmask_b32_e64 v2, v169, v2, s[24:25]
	v_cndmask_b32_e64 v3, v169, v3, s[28:29]
	v_cndmask_b32_e64 v4, v169, v4, s[30:31]
	v_cndmask_b32_e64 v5, v169, v5, s[34:35]
	v_cndmask_b32_e64 v148, v169, v148, s[36:37]
	v_cndmask_b32_e64 v149, v169, v149, s[38:39]
	v_cndmask_b32_e64 v150, v169, v150, s[40:41]
	v_cndmask_b32_e64 v151, v169, v151, s[42:43]
	v_cndmask_b32_e64 v10, v169, v10, s[44:45]
	v_cndmask_b32_e64 v11, v169, v11, s[46:47]
	v_cndmask_b32_e64 v12, v169, v12, s[48:49]
	v_cndmask_b32_e64 v13, v169, v13, s[0:1]

.LBB0_1678:
	v_fmac_f32_e32 v148, v193, v18
	v_fmac_f32_e32 v195, v19, v16
	v_cvt_pk_bf16_f32 v198, v0, v1
	v_cvt_pk_bf16_f32 v199, v2, v3
	v_cvt_pk_bf16_f32 v200, v4, v5
	v_cvt_pk_bf16_f32 v201, v6, v7
	s_nop 1
	ds_read_b128 v[202:205], v191 offset:20480
	ds_read_b128 v[206:209], v191 offset:22528
	ds_read_b128 v[210:213], v191 offset:24576
	ds_read_b128 v[214:217], v191 offset:26624
	ds_read_b128 v[222:225], v191 offset:28672
	ds_read_b128 v[226:229], v191 offset:30720
	ds_read_b128 v[0:3], v191 offset:16384
	ds_read_b128 v[4:7], v191 offset:18432
	s_waitcnt lgkmcnt(7)
	v_mfma_f32_16x16x32_bf16 v[72:75], v[202:205], v[198:201], v[72:75]
	s_waitcnt lgkmcnt(6)
	v_mfma_f32_16x16x32_bf16 v[68:71], v[206:209], v[198:201], v[68:71]
	s_waitcnt lgkmcnt(5)
	v_mfma_f32_16x16x32_bf16 v[64:67], v[210:213], v[198:201], v[64:67]
	s_waitcnt lgkmcnt(4)
	v_mfma_f32_16x16x32_bf16 v[60:63], v[214:217], v[198:201], v[60:63]
	s_waitcnt lgkmcnt(3)
	v_mfma_f32_16x16x32_bf16 v[56:59], v[222:225], v[198:201], v[56:59]
	s_waitcnt lgkmcnt(2)
	v_mfma_f32_16x16x32_bf16 v[52:55], v[226:229], v[198:201], v[52:55]
	s_waitcnt lgkmcnt(1)
	v_mfma_f32_16x16x32_bf16 v[0:3], v[0:3], v[198:201], v[80:83]
	s_waitcnt lgkmcnt(0)
	v_mfma_f32_16x16x32_bf16 v[4:7], v[4:7], v[198:201], v[76:79]
	v_cvt_pk_bf16_f32 v198, v8, v9
	v_cvt_pk_bf16_f32 v199, v10, v11
	v_cvt_pk_bf16_f32 v200, v12, v13
	v_cvt_pk_bf16_f32 v201, v14, v15
	s_nop 1
	ds_read_b128 v[8:11], v192 offset:16384
	ds_read_b128 v[12:15], v192 offset:18432
	ds_read_b128 v[202:205], v192 offset:20480
	ds_read_b128 v[206:209], v192 offset:22528
	ds_read_b128 v[210:213], v192 offset:24576
	ds_read_b128 v[214:217], v192 offset:26624
	ds_read_b128 v[222:225], v192 offset:28672
	ds_read_b128 v[226:229], v192 offset:30720
	s_waitcnt lgkmcnt(7)
	v_mfma_f32_16x16x32_bf16 v[80:83], v[8:11], v[198:201], v[0:3]
	s_waitcnt lgkmcnt(6)
	v_mfma_f32_16x16x32_bf16 v[76:79], v[12:15], v[198:201], v[4:7]
	s_waitcnt lgkmcnt(5)
	v_mfma_f32_16x16x32_bf16 v[72:75], v[202:205], v[198:201], v[72:75]
	s_waitcnt lgkmcnt(4)
	v_mfma_f32_16x16x32_bf16 v[68:71], v[206:209], v[198:201], v[68:71]
	s_waitcnt lgkmcnt(3)
	v_mfma_f32_16x16x32_bf16 v[64:67], v[210:213], v[198:201], v[64:67]
	s_waitcnt lgkmcnt(2)
	v_mfma_f32_16x16x32_bf16 v[60:63], v[214:217], v[198:201], v[60:63]
	s_waitcnt lgkmcnt(1)
	v_mfma_f32_16x16x32_bf16 v[56:59], v[222:225], v[198:201], v[56:59]
	s_waitcnt lgkmcnt(0)
	v_mfma_f32_16x16x32_bf16 v[52:55], v[226:229], v[198:201], v[52:55]
	s_andn2_b64 vcc, exec, s[12:13]
	s_add_i32 s11, s11, 64
	s_cbranch_vccz .Lwin_exit
	v_mov_b32_e32 v194, v197
	v_mov_b32_e32 v16, v196
	v_mov_b32_e32 v193, v148
	v_mov_b32_e32 v19, v195
	s_branch .Lwinb_1658
.Lwinb_1658:
	s_waitcnt vmcnt(0) lgkmcnt(0)
	s_barrier
	ds_read_b128 v[0:3], v165 offset:32768
	ds_read_b128 v[4:7], v166 offset:32768
	ds_read_b128 v[8:11], v167 offset:32768
	ds_read_b128 v[12:15], v175 offset:32768
	ds_read_b128 v[124:127], v176 offset:32768
	ds_read_b128 v[132:135], v177 offset:32768
	ds_read_b128 v[144:147], v178 offset:32768
	ds_read_b128 v[148:151], v179 offset:32768
	s_waitcnt lgkmcnt(7)
	v_mfma_f32_16x16x32_bf16 v[0:3], v[0:3], v[20:23], 0
	s_mov_b32 s0, s10
	s_add_i32 s10, s10, 1
	s_cmp_ge_i32 s0, s86
	s_waitcnt lgkmcnt(6)
	v_mfma_f32_16x16x32_bf16 v[4:7], v[4:7], v[20:23], 0
	s_cselect_b64 s[12:13], -1, 0
	s_cmp_lt_i32 s0, s86
	s_cselect_b32 s56, s10, s0
	s_waitcnt lgkmcnt(5)
	v_mfma_f32_16x16x32_bf16 v[0:3], v[8:11], v[24:27], v[0:3]
	s_lshl_b64 s[0:1], s[56:57], 14
	v_readfirstlane_b32 vcc_lo, v143
	s_mov_b32 m0, vcc_lo
	v_lshl_add_u64 v[140:141], v[116:117], 0, s[0:1]
	global_load_lds_dwordx4 v[140:141], off
	s_add_u32 m0, m0, 0x1000
	v_lshl_add_u64 v[140:141], v[118:119], 0, s[0:1]
	global_load_lds_dwordx4 v[140:141], off
	s_add_u32 m0, m0, 0x1000
	v_lshl_add_u64 v[140:141], v[120:121], 0, s[0:1]
	global_load_lds_dwordx4 v[140:141], off
	s_add_u32 m0, m0, 0x1000
	v_lshl_add_u64 v[140:141], v[122:123], 0, s[0:1]
	global_load_lds_dwordx4 v[140:141], off
	s_add_u32 m0, m0, 0x1000
	v_lshl_add_u64 v[140:141], v[128:129], 0, s[0:1]
	global_load_lds_dwordx4 v[140:141], off
	s_add_u32 m0, m0, 0x1000
	v_lshl_add_u64 v[140:141], v[130:131], 0, s[0:1]
	global_load_lds_dwordx4 v[140:141], off
	s_add_u32 m0, m0, 0x1000
	v_lshl_add_u64 v[140:141], v[136:137], 0, s[0:1]
	global_load_lds_dwordx4 v[140:141], off
	s_add_u32 m0, m0, 0x1000
	v_lshl_add_u64 v[140:141], v[138:139], 0, s[0:1]
	global_load_lds_dwordx4 v[140:141], off
	s_waitcnt lgkmcnt(4)
	v_mfma_f32_16x16x32_bf16 v[4:7], v[12:15], v[24:27], v[4:7]
	s_waitcnt lgkmcnt(3)
	v_mfma_f32_16x16x32_bf16 v[0:3], v[124:127], v[28:31], v[0:3]
	s_waitcnt lgkmcnt(2)
	v_mfma_f32_16x16x32_bf16 v[10:13], v[132:135], v[28:31], v[4:7]
	s_waitcnt lgkmcnt(1)
	v_mfma_f32_16x16x32_bf16 v[6:9], v[144:147], v[32:35], v[0:3]
	s_waitcnt lgkmcnt(0)
	v_mfma_f32_16x16x32_bf16 v[2:5], v[148:151], v[32:35], v[10:13]
	s_nop 2
	ds_read_b128 v[10:13], v165 offset:40960
	ds_read_b128 v[148:151], v180 offset:32768
	ds_read_b128 v[196:199], v167 offset:40960
	ds_read_b128 v[200:203], v181 offset:32768
	ds_read_b128 v[204:207], v176 offset:40960
	ds_read_b128 v[208:211], v182 offset:32768
	ds_read_b128 v[212:215], v178 offset:40960
	ds_read_b128 v[216:219], v183 offset:32768
	s_waitcnt lgkmcnt(7)
	v_mfma_f32_16x16x32_bf16 v[10:13], v[10:13], v[20:23], 0
	s_waitcnt lgkmcnt(6)
	v_mfma_f32_16x16x32_bf16 v[148:151], v[148:151], v[20:23], 0
	s_waitcnt lgkmcnt(5)
	v_mfma_f32_16x16x32_bf16 v[10:13], v[196:199], v[24:27], v[10:13]
	s_waitcnt lgkmcnt(4)
	v_mfma_f32_16x16x32_bf16 v[148:151], v[200:203], v[24:27], v[148:151]
	s_waitcnt lgkmcnt(3)
	v_mfma_f32_16x16x32_bf16 v[10:13], v[204:207], v[28:31], v[10:13]
	s_waitcnt lgkmcnt(2)
	v_mfma_f32_16x16x32_bf16 v[196:199], v[208:211], v[28:31], v[148:151]
	s_waitcnt lgkmcnt(1)
	v_mfma_f32_16x16x32_bf16 v[148:151], v[212:215], v[32:35], v[10:13]
	s_waitcnt lgkmcnt(0)
	v_mfma_f32_16x16x32_bf16 v[10:13], v[216:219], v[32:35], v[196:199]
	s_add_i32 s0, s11, 63
	v_cmp_gt_i32_e32 vcc, s0, v164
	v_cmp_le_i32_e64 s[0:1], s11, v184
	v_add_u32_e32 v205, s11, v187
	s_or_b64 s[14:15], vcc, s[0:1]
	s_and_saveexec_b64 s[26:27], s[14:15]
	s_xor_b64 s[26:27], exec, s[26:27]
	s_cbranch_execz .Lwinb_1660
	v_add_u32_e32 v209, 2, v205
	v_add_u32_e32 v208, 3, v205
	v_add_u32_e32 v207, 4, v205
	v_add_u32_e32 v206, 5, v205
	v_add_u32_e32 v204, 6, v205
	v_add_u32_e32 v203, 7, v205
	v_add_u32_e32 v202, 32, v205
	v_add_u32_e32 v201, 34, v205
	v_add_u32_e32 v200, 35, v205
	v_add_u32_e32 v199, 36, v205
	v_add_u32_e32 v198, 37, v205
	v_add_u32_e32 v197, 38, v205
	v_add_u32_e32 v18, 39, v205
	v_cmp_gt_i32_e32 vcc, v205, v186
	v_cmp_le_i32_e64 s[0:1], v205, v185
	s_and_b64 s[16:17], vcc, s[0:1]
	v_cmp_ge_i32_e32 vcc, v205, v186
	v_cmp_lt_i32_e64 s[0:1], v205, v185
	s_and_b64 s[18:19], vcc, s[0:1]
	v_cmp_gt_i32_e32 vcc, v209, v186
	v_cmp_le_i32_e64 s[0:1], v209, v185
	s_and_b64 s[20:21], vcc, s[0:1]
	v_cmp_gt_i32_e32 vcc, v208, v186
	v_cmp_le_i32_e64 s[0:1], v208, v185
	s_and_b64 s[22:23], vcc, s[0:1]
	v_cmp_gt_i32_e32 vcc, v207, v186
	v_cmp_le_i32_e64 s[0:1], v207, v185
	s_and_b64 s[24:25], vcc, s[0:1]
	v_cmp_gt_i32_e32 vcc, v206, v186
	v_cmp_le_i32_e64 s[0:1], v206, v185
	s_and_b64 s[28:29], vcc, s[0:1]
	v_cmp_gt_i32_e32 vcc, v204, v186
	v_cmp_le_i32_e64 s[0:1], v204, v185
	s_and_b64 s[30:31], vcc, s[0:1]
	v_cmp_gt_i32_e32 vcc, v203, v186
	v_cmp_le_i32_e64 s[0:1], v203, v185
	s_and_b64 s[34:35], vcc, s[0:1]
	v_cmp_gt_i32_e32 vcc, v202, v186
	v_cmp_le_i32_e64 s[0:1], v202, v185
	s_and_b64 s[36:37], vcc, s[0:1]
	v_cmp_ge_i32_e32 vcc, v202, v186
	v_cmp_lt_i32_e64 s[0:1], v202, v185
	s_and_b64 s[38:39], vcc, s[0:1]
	v_cmp_gt_i32_e32 vcc, v201, v186
	v_cmp_le_i32_e64 s[0:1], v201, v185
	s_and_b64 s[40:41], vcc, s[0:1]
	v_cmp_gt_i32_e32 vcc, v200, v186
	v_cmp_le_i32_e64 s[0:1], v200, v185
	s_and_b64 s[42:43], vcc, s[0:1]
	v_cmp_gt_i32_e32 vcc, v199, v186
	v_cmp_le_i32_e64 s[0:1], v199, v185
	s_and_b64 s[44:45], vcc, s[0:1]
	v_cmp_gt_i32_e32 vcc, v198, v186
	v_cmp_le_i32_e64 s[0:1], v198, v185
	s_and_b64 s[46:47], vcc, s[0:1]
	v_cmp_gt_i32_e32 vcc, v197, v186
	v_cmp_le_i32_e64 s[0:1], v197, v185
	s_and_b64 s[48:49], vcc, s[0:1]
	v_cmp_gt_i32_e32 vcc, v18, v186
	v_cmp_le_i32_e64 s[0:1], v18, v185
	s_and_b64 s[0:1], vcc, s[0:1]
	v_cndmask_b32_e64 v6, v169, v6, s[16:17]
	v_cndmask_b32_e64 v7, v169, v7, s[18:19]
	v_cndmask_b32_e64 v8, v169, v8, s[20:21]
	v_cndmask_b32_e64 v9, v169, v9, s[22:23]
	v_cndmask_b32_e64 v2, v169, v2, s[24:25]
	v_cndmask_b32_e64 v3, v169, v3, s[28:29]
	v_cndmask_b32_e64 v4, v169, v4, s[30:31]
	v_cndmask_b32_e64 v5, v169, v5, s[34:35]
	v_cndmask_b32_e64 v148, v169, v148, s[36:37]
	v_cndmask_b32_e64 v149, v169, v149, s[38:39]
	v_cndmask_b32_e64 v150, v169, v150, s[40:41]
	v_cndmask_b32_e64 v151, v169, v151, s[42:43]
	v_cndmask_b32_e64 v10, v169, v10, s[44:45]
	v_cndmask_b32_e64 v11, v169, v11, s[46:47]
	v_cndmask_b32_e64 v12, v169, v12, s[48:49]
	v_cndmask_b32_e64 v13, v169, v13, s[0:1]

.Lwinb_1668:
	v_cvt_pk_bf16_f32 v148, v0, v1
	v_cvt_pk_bf16_f32 v149, v2, v3
	v_cvt_pk_bf16_f32 v150, v4, v5
	v_cvt_pk_bf16_f32 v151, v6, v7
	s_nop 1
	ds_read_b128 v[0:3], v191 offset:49152
	ds_read_b128 v[4:7], v191 offset:51200
	ds_read_b128 v[210:213], v191 offset:53248
	ds_read_b128 v[214:217], v191 offset:55296
	ds_read_b128 v[222:225], v191 offset:57344
	ds_read_b128 v[226:229], v191 offset:59392
	ds_read_b128 v[230:233], v191 offset:61440
	ds_read_b128 v[234:237], v191 offset:63488
	s_waitcnt lgkmcnt(7)
	v_mfma_f32_16x16x32_bf16 v[0:3], v[0:3], v[148:151], v[112:115]
	s_waitcnt lgkmcnt(6)
	v_mfma_f32_16x16x32_bf16 v[4:7], v[4:7], v[148:151], v[108:111]
	s_waitcnt lgkmcnt(5)
	v_mfma_f32_16x16x32_bf16 v[104:107], v[210:213], v[148:151], v[104:107]
	s_waitcnt lgkmcnt(4)
	v_mfma_f32_16x16x32_bf16 v[100:103], v[214:217], v[148:151], v[100:103]
	s_waitcnt lgkmcnt(3)
	v_mfma_f32_16x16x32_bf16 v[96:99], v[222:225], v[148:151], v[96:99]
	s_waitcnt lgkmcnt(2)
	v_mfma_f32_16x16x32_bf16 v[92:95], v[226:229], v[148:151], v[92:95]
	s_waitcnt lgkmcnt(1)
	v_mfma_f32_16x16x32_bf16 v[88:91], v[230:233], v[148:151], v[88:91]
	s_waitcnt lgkmcnt(0)
	v_mfma_f32_16x16x32_bf16 v[84:87], v[234:237], v[148:151], v[84:87]
	v_cvt_pk_bf16_f32 v148, v8, v9
	v_cvt_pk_bf16_f32 v149, v10, v11
	v_cvt_pk_bf16_f32 v150, v12, v13
	v_cvt_pk_bf16_f32 v151, v14, v15
	s_nop 1
	ds_read_b128 v[8:11], v192 offset:49152
	ds_read_b128 v[12:15], v192 offset:51200
	ds_read_b128 v[210:213], v192 offset:53248
	ds_read_b128 v[214:217], v192 offset:55296
	ds_read_b128 v[222:225], v192 offset:57344
	ds_read_b128 v[226:229], v192 offset:59392
	ds_read_b128 v[230:233], v192 offset:61440
	ds_read_b128 v[234:237], v192 offset:63488
	s_waitcnt lgkmcnt(7)
	v_mfma_f32_16x16x32_bf16 v[112:115], v[8:11], v[148:151], v[0:3]
	s_waitcnt lgkmcnt(6)
	v_mfma_f32_16x16x32_bf16 v[108:111], v[12:15], v[148:151], v[4:7]
	s_waitcnt lgkmcnt(5)
	v_mfma_f32_16x16x32_bf16 v[104:107], v[210:213], v[148:151], v[104:107]
	s_waitcnt lgkmcnt(4)
	v_mfma_f32_16x16x32_bf16 v[100:103], v[214:217], v[148:151], v[100:103]
	s_waitcnt lgkmcnt(3)
	v_mfma_f32_16x16x32_bf16 v[96:99], v[222:225], v[148:151], v[96:99]
	s_waitcnt lgkmcnt(2)
	v_mfma_f32_16x16x32_bf16 v[92:95], v[226:229], v[148:151], v[92:95]
	s_waitcnt lgkmcnt(1)
	v_mfma_f32_16x16x32_bf16 v[88:91], v[230:233], v[148:151], v[88:91]
	s_waitcnt lgkmcnt(0)
	v_mfma_f32_16x16x32_bf16 v[84:87], v[234:237], v[148:151], v[84:87]
	ds_read_b128 v[0:3], v165 offset:32768
	ds_read_b128 v[4:7], v166 offset:32768
	ds_read_b128 v[8:11], v167 offset:32768
	ds_read_b128 v[12:15], v175 offset:32768
	ds_read_b128 v[148:151], v176 offset:32768
	ds_read_b128 v[210:213], v177 offset:32768
	ds_read_b128 v[214:217], v178 offset:32768
	ds_read_b128 v[222:225], v179 offset:32768
	s_waitcnt lgkmcnt(7)
	v_mfma_f32_16x16x32_bf16 v[0:3], v[0:3], v[36:39], 0
	s_waitcnt lgkmcnt(6)
	v_mfma_f32_16x16x32_bf16 v[4:7], v[4:7], v[36:39], 0
	s_waitcnt lgkmcnt(5)
	v_mfma_f32_16x16x32_bf16 v[0:3], v[8:11], v[40:43], v[0:3]
	s_waitcnt lgkmcnt(4)
	v_mfma_f32_16x16x32_bf16 v[4:7], v[12:15], v[40:43], v[4:7]
	s_waitcnt lgkmcnt(3)
	v_mfma_f32_16x16x32_bf16 v[0:3], v[148:151], v[44:47], v[0:3]
	s_waitcnt lgkmcnt(2)
	v_mfma_f32_16x16x32_bf16 v[10:13], v[210:213], v[44:47], v[4:7]
	s_waitcnt lgkmcnt(1)
	v_mfma_f32_16x16x32_bf16 v[6:9], v[214:217], v[48:51], v[0:3]
	s_waitcnt lgkmcnt(0)
	v_mfma_f32_16x16x32_bf16 v[2:5], v[222:225], v[48:51], v[10:13]
	s_nop 3
	ds_read_b128 v[10:13], v165 offset:40960
	ds_read_b128 v[148:151], v180 offset:32768
	ds_read_b128 v[210:213], v167 offset:40960
	ds_read_b128 v[214:217], v181 offset:32768
	ds_read_b128 v[222:225], v176 offset:40960
	ds_read_b128 v[226:229], v182 offset:32768
	ds_read_b128 v[230:233], v178 offset:40960
	ds_read_b128 v[234:237], v183 offset:32768
	s_waitcnt lgkmcnt(7)
	v_mfma_f32_16x16x32_bf16 v[10:13], v[10:13], v[36:39], 0
	s_waitcnt lgkmcnt(6)
	v_mfma_f32_16x16x32_bf16 v[148:151], v[148:151], v[36:39], 0
	s_waitcnt lgkmcnt(5)
	v_mfma_f32_16x16x32_bf16 v[10:13], v[210:213], v[40:43], v[10:13]
	s_waitcnt lgkmcnt(4)
	v_mfma_f32_16x16x32_bf16 v[148:151], v[214:217], v[40:43], v[148:151]
	s_waitcnt lgkmcnt(3)
	v_mfma_f32_16x16x32_bf16 v[10:13], v[222:225], v[44:47], v[10:13]
	s_waitcnt lgkmcnt(2)
	v_mfma_f32_16x16x32_bf16 v[210:213], v[226:229], v[44:47], v[148:151]
	s_waitcnt lgkmcnt(1)
	v_mfma_f32_16x16x32_bf16 v[148:151], v[230:233], v[48:51], v[10:13]
	s_waitcnt lgkmcnt(0)
	v_mfma_f32_16x16x32_bf16 v[10:13], v[234:237], v[48:51], v[210:213]
	s_add_i32 s0, s11, 59
	v_cmp_gt_i32_e32 vcc, s0, v164
	v_cmp_le_i32_e64 s[0:1], s11, v188
	s_or_b64 s[14:15], vcc, s[0:1]
	s_and_saveexec_b64 s[26:27], s[14:15]
	s_xor_b64 s[26:27], exec, s[26:27]
	s_cbranch_execz .Lwinb_1670
	v_add_u32_e32 v209, 2, v205
	v_add_u32_e32 v208, 3, v205
	v_add_u32_e32 v207, 4, v205
	v_add_u32_e32 v206, 5, v205
	v_add_u32_e32 v204, 6, v205
	v_add_u32_e32 v203, 7, v205
	v_add_u32_e32 v202, 32, v205
	v_add_u32_e32 v201, 34, v205
	v_add_u32_e32 v200, 35, v205
	v_add_u32_e32 v199, 36, v205
	v_add_u32_e32 v198, 37, v205
	v_add_u32_e32 v197, 38, v205
	v_add_u32_e32 v18, 39, v205
	v_cmp_gt_i32_e32 vcc, v205, v190
	v_cmp_le_i32_e64 s[0:1], v205, v189
	s_and_b64 s[16:17], vcc, s[0:1]
	v_cmp_ge_i32_e32 vcc, v205, v190
	v_cmp_lt_i32_e64 s[0:1], v205, v189
	s_and_b64 s[18:19], vcc, s[0:1]
	v_cmp_gt_i32_e32 vcc, v209, v190
	v_cmp_le_i32_e64 s[0:1], v209, v189
	s_and_b64 s[20:21], vcc, s[0:1]
	v_cmp_gt_i32_e32 vcc, v208, v190
	v_cmp_le_i32_e64 s[0:1], v208, v189
	s_and_b64 s[22:23], vcc, s[0:1]
	v_cmp_gt_i32_e32 vcc, v207, v190
	v_cmp_le_i32_e64 s[0:1], v205, v185
	s_and_b64 s[24:25], s[0:1], vcc
	v_cmp_gt_i32_e32 vcc, v206, v190
	v_cmp_le_i32_e64 s[0:1], v206, v189
	s_and_b64 s[28:29], vcc, s[0:1]
	v_cmp_gt_i32_e32 vcc, v204, v190
	v_cmp_le_i32_e64 s[0:1], v204, v189
	s_and_b64 s[30:31], vcc, s[0:1]
	v_cmp_gt_i32_e32 vcc, v203, v190
	v_cmp_le_i32_e64 s[0:1], v203, v189
	s_and_b64 s[34:35], vcc, s[0:1]
	v_cmp_gt_i32_e32 vcc, v202, v190
	v_cmp_le_i32_e64 s[0:1], v202, v189
	s_and_b64 s[36:37], vcc, s[0:1]
	v_cmp_ge_i32_e32 vcc, v202, v190
	v_cmp_lt_i32_e64 s[0:1], v202, v189
	s_and_b64 s[38:39], vcc, s[0:1]
	v_cmp_gt_i32_e32 vcc, v201, v190
	v_cmp_le_i32_e64 s[0:1], v201, v189
	s_and_b64 s[40:41], vcc, s[0:1]
	v_cmp_gt_i32_e32 vcc, v200, v190
	v_cmp_le_i32_e64 s[0:1], v200, v189
	s_and_b64 s[42:43], vcc, s[0:1]
	v_cmp_gt_i32_e32 vcc, v199, v190
	v_cmp_le_i32_e64 s[0:1], v199, v189
	s_and_b64 s[44:45], vcc, s[0:1]
	v_cmp_gt_i32_e32 vcc, v198, v190
	v_cmp_le_i32_e64 s[0:1], v198, v189
	s_and_b64 s[46:47], vcc, s[0:1]
	v_cmp_gt_i32_e32 vcc, v197, v190
	v_cmp_le_i32_e64 s[0:1], v197, v189
	s_and_b64 s[48:49], vcc, s[0:1]
	v_cmp_gt_i32_e32 vcc, v18, v190
	v_cmp_le_i32_e64 s[0:1], v18, v189
	s_and_b64 s[0:1], vcc, s[0:1]
	v_cndmask_b32_e64 v6, v169, v6, s[16:17]
	v_cndmask_b32_e64 v7, v169, v7, s[18:19]
	v_cndmask_b32_e64 v8, v169, v8, s[20:21]
	v_cndmask_b32_e64 v9, v169, v9, s[22:23]
	v_cndmask_b32_e64 v2, v169, v2, s[24:25]
	v_cndmask_b32_e64 v3, v169, v3, s[28:29]
	v_cndmask_b32_e64 v4, v169, v4, s[30:31]
	v_cndmask_b32_e64 v5, v169, v5, s[34:35]
	v_cndmask_b32_e64 v148, v169, v148, s[36:37]
	v_cndmask_b32_e64 v149, v169, v149, s[38:39]
	v_cndmask_b32_e64 v150, v169, v150, s[40:41]
	v_cndmask_b32_e64 v151, v169, v151, s[42:43]
	v_cndmask_b32_e64 v10, v169, v10, s[44:45]
	v_cndmask_b32_e64 v11, v169, v11, s[46:47]
	v_cndmask_b32_e64 v12, v169, v12, s[48:49]
	v_cndmask_b32_e64 v13, v169, v13, s[0:1]

.Lwinb_1678:
	v_fmac_f32_e32 v148, v193, v18
	v_fmac_f32_e32 v195, v19, v16
	v_cvt_pk_bf16_f32 v198, v0, v1
	v_cvt_pk_bf16_f32 v199, v2, v3
	v_cvt_pk_bf16_f32 v200, v4, v5
	v_cvt_pk_bf16_f32 v201, v6, v7
	s_nop 1
	ds_read_b128 v[202:205], v191 offset:53248
	ds_read_b128 v[206:209], v191 offset:55296
	ds_read_b128 v[210:213], v191 offset:57344
	ds_read_b128 v[214:217], v191 offset:59392
	ds_read_b128 v[222:225], v191 offset:61440
	ds_read_b128 v[226:229], v191 offset:63488
	ds_read_b128 v[0:3], v191 offset:49152
	ds_read_b128 v[4:7], v191 offset:51200
	s_waitcnt lgkmcnt(7)
	v_mfma_f32_16x16x32_bf16 v[72:75], v[202:205], v[198:201], v[72:75]
	s_waitcnt lgkmcnt(6)
	v_mfma_f32_16x16x32_bf16 v[68:71], v[206:209], v[198:201], v[68:71]
	s_waitcnt lgkmcnt(5)
	v_mfma_f32_16x16x32_bf16 v[64:67], v[210:213], v[198:201], v[64:67]
	s_waitcnt lgkmcnt(4)
	v_mfma_f32_16x16x32_bf16 v[60:63], v[214:217], v[198:201], v[60:63]
	s_waitcnt lgkmcnt(3)
	v_mfma_f32_16x16x32_bf16 v[56:59], v[222:225], v[198:201], v[56:59]
	s_waitcnt lgkmcnt(2)
	v_mfma_f32_16x16x32_bf16 v[52:55], v[226:229], v[198:201], v[52:55]
	s_waitcnt lgkmcnt(1)
	v_mfma_f32_16x16x32_bf16 v[0:3], v[0:3], v[198:201], v[80:83]
	s_waitcnt lgkmcnt(0)
	v_mfma_f32_16x16x32_bf16 v[4:7], v[4:7], v[198:201], v[76:79]
	v_cvt_pk_bf16_f32 v198, v8, v9
	v_cvt_pk_bf16_f32 v199, v10, v11
	v_cvt_pk_bf16_f32 v200, v12, v13
	v_cvt_pk_bf16_f32 v201, v14, v15
	s_nop 1
	ds_read_b128 v[8:11], v192 offset:49152
	ds_read_b128 v[12:15], v192 offset:51200
	ds_read_b128 v[202:205], v192 offset:53248
	ds_read_b128 v[206:209], v192 offset:55296
	ds_read_b128 v[210:213], v192 offset:57344
	ds_read_b128 v[214:217], v192 offset:59392
	ds_read_b128 v[222:225], v192 offset:61440
	ds_read_b128 v[226:229], v192 offset:63488
	s_waitcnt lgkmcnt(7)
	v_mfma_f32_16x16x32_bf16 v[80:83], v[8:11], v[198:201], v[0:3]
	s_waitcnt lgkmcnt(6)
	v_mfma_f32_16x16x32_bf16 v[76:79], v[12:15], v[198:201], v[4:7]
	s_waitcnt lgkmcnt(5)
	v_mfma_f32_16x16x32_bf16 v[72:75], v[202:205], v[198:201], v[72:75]
	s_waitcnt lgkmcnt(4)
	v_mfma_f32_16x16x32_bf16 v[68:71], v[206:209], v[198:201], v[68:71]
	s_waitcnt lgkmcnt(3)
	v_mfma_f32_16x16x32_bf16 v[64:67], v[210:213], v[198:201], v[64:67]
	s_waitcnt lgkmcnt(2)
	v_mfma_f32_16x16x32_bf16 v[60:63], v[214:217], v[198:201], v[60:63]
	s_waitcnt lgkmcnt(1)
	v_mfma_f32_16x16x32_bf16 v[56:59], v[222:225], v[198:201], v[56:59]
	s_waitcnt lgkmcnt(0)
	v_mfma_f32_16x16x32_bf16 v[52:55], v[226:229], v[198:201], v[52:55]
	s_andn2_b64 vcc, exec, s[12:13]
	s_add_i32 s11, s11, 64
	s_cbranch_vccz .Lwin_exit
	v_mov_b32_e32 v194, v197
	v_mov_b32_e32 v16, v196
	v_mov_b32_e32 v193, v148
	v_mov_b32_e32 v19, v195
	s_branch .LBB0_1658
.Lwin_exit:
	s_waitcnt vmcnt(0)
	s_barrier
	s_branch .LBB0_1467
